# delta scan: conv carry rows kept in registers (no LDS-to-LDS copy), step prologue LDS loads hoisted above prefetch, dead q.k dot removed
# speedup vs baseline: 1.0892x; 1.0001x over previous
; __device__ __forceinline__ float bflo(unsigned u) { return __uint_as_float(u << 16); }
; __device__ __forceinline__ float bfhi(unsigned u) { return __uint_as_float(u & 0xffff0000u); }
; template <int MIX>
; __device__ __forceinline__ void scan_part(const Params& p, const int layer, const int smp, const int b0, const int bstep, const int bend, const int h, const int part, char* lds, const int tid) {
;     ...
;   for (int t0 = 0; t0 < T; t0 += 32) {
;     const int ntok = min(32, T - t0);
;     ntok_last = ntok;
;     const bool valid = tt < ntok;
;     float* dst = qkdv + tt * 256;
;     if (MIX != 0 && valid) {
;       if (VN == 4) *(f32x4*)(dst + 192 + sub * 4) = (f32x4){bflo(R2.x), bfhi(R2.x), bflo(R2.y), bfhi(R2.y)};
;       else *(float2*)(dst + 192 + sub * 2) = make_float2(bflo(R2.x), bfhi(R2.x));
;     }
;     if (MIX == 0) {
;       if (valid) {
;         *(uint4*)(rawb + (3 + tt) * RS + 0 + sub * 8) = R0;
;         *(uint4*)(rawb + (3 + tt) * RS + 64 + sub * 8) = R1;
;         if (VN == 4) *(uint2*)(rawb + (3 + tt) * RS + 128 + sub * 4) = R2;
;         else *(unsigned*)(rawb + (3 + tt) * RS + 128 + sub * 2) = R2.x;
;       }
;     ...
;     if (MIX == 0 && t0 + 32 < T) {
;       if (tid < 3 * RS / 8) { const uint4 v = *(const uint4*)(rawb + 32 * RS + tid * 8); *(uint4*)(rawb + tid * 8) = v; }
;     }
.LBB0_421:
	s_sub_i32 s26, 0x810, s23
	s_min_u32 s26, s26, 32
	s_waitcnt vmcnt(2)
	s_cmp_eq_u32 s23, 0
	s_cbranch_scc1 .Ldcarry_skip
	v_cmp_lt_i32_e64 s[42:43], 28, v131
	s_and_saveexec_b64 s[44:45], s[42:43]
	s_cbranch_execz .Ldcarry_none
	ds_write_b128 v139, v[240:243] offset:29024
	ds_write_b128 v139, v[244:247] offset:29152
	ds_write_b32 v150, v248 offset:29280

; __device__ __forceinline__ float bflo(unsigned u) { return __uint_as_float(u << 16); }
; __device__ __forceinline__ float bfhi(unsigned u) { return __uint_as_float(u & 0xffff0000u); }
; __device__ __forceinline__ float siluf_(float x) { return x * __builtin_amdgcn_rcpf(1.0f + __expf(-x)); }
; template <int N, int RS>
; __device__ __forceinline__ void convN(const bf16_t* rawb, const float (&w)[4][N], int tt, int off, float (&x)[N]) {
; #pragma unroll
;   for (int i = 0; i < N; ++i) x[i] = 0.f;
; #pragma unroll
;   for (int j = 0; j < 4; ++j) {
;     float xv[N];
;     if (N == 8) { const uint4 rv = *(const uint4*)(rawb + (tt + j) * RS + off); unpack8(rv, xv); }
;     else if (N == 4) { const uint2 rv = *(const uint2*)(rawb + (tt + j) * RS + off); xv[0] = bflo(rv.x); xv[1] = bfhi(rv.x); xv[2 % N] = bflo(rv.y); xv[3 % N] = bfhi(rv.y); }
;     else { const unsigned rv = *(const unsigned*)(rawb + (tt + j) * RS + off); xv[0] = bflo(rv); xv[1] = bfhi(rv); }
; #pragma unroll
;     for (int i = 0; i < N; ++i) x[i] += w[j][i] * xv[i];
;   }
;   if (N == 2) {
; #pragma unroll
;     for (int i = 0; i < N; ++i) asm volatile("" : "+v"(x[i]));
;   }
; #pragma unroll
;   for (int i = 0; i < N; ++i) x[i] = siluf_(x[i]);
; }
; template <int MIX>
; __device__ __forceinline__ void scan_part(const Params& p, const int layer, const int smp, const int b0, const int bstep, const int bend, const int h, const int part, char* lds, const int tid) {
;     ...
;     if (MIX == 0) {
;       if (valid) {
;         *(uint4*)(rawb + (3 + tt) * RS + 0 + sub * 8) = R0;
;         *(uint4*)(rawb + (3 + tt) * RS + 64 + sub * 8) = R1;
;         if (VN == 4) *(uint2*)(rawb + (3 + tt) * RS + 128 + sub * 4) = R2;
;         else *(unsigned*)(rawb + (3 + tt) * RS + 128 + sub * 2) = R2.x;
;       }
;       __syncthreads();
;       if (valid) {
;         float xq[8], xk[8], xv[VN];
;         { float cwv[4][VN];
; #pragma unroll
;           for (int j = 0; j < 4; ++j)
; #pragma unroll
;             for (int i = 0; i < VN; ++i) cwv[j][i] = cwl[j * RS + 128 + sub * VN + i];
;           convN<VN, RS>(rawb, cwv, tt, 128 + sub * VN, xv); }
;         convN<8, RS>(rawb, cwq, tt, sub * 8, xq);
;         convN<8, RS>(rawb, cwk, tt, 64 + sub * 8, xk);
.Ldcarry_skip:
	v_cmp_gt_i32_e64 s[42:43], s26, v131
	s_and_saveexec_b64 s[44:45], s[42:43]
	s_cbranch_execz .LBB0_423
	ds_write_b128 v139, v[68:71] offset:38240
	ds_write_b128 v139, v[72:75] offset:38368
	ds_write_b32 v150, v97 offset:38496
.LBB0_423:
	s_or_b64 exec, exec, s[44:45]
	v_mov_b64_e32 v[240:241], v[68:69]
	v_mov_b64_e32 v[242:243], v[70:71]
	v_mov_b64_e32 v[244:245], v[72:73]
	v_mov_b64_e32 v[246:247], v[74:75]
	v_mov_b32_e32 v248, v97
	s_waitcnt lgkmcnt(0)
	s_barrier
	s_and_saveexec_b64 s[50:51], s[42:43]
	s_cbranch_execz .LBB0_426
	v_add_u32_e32 v2, v140, v138
	v_add_u32_e32 v0, 0x9200, v2
	v_add_u32_e32 v76, 0xbc00, v137
	ds_read2_b32 v[0:1], v0 offset0:64 offset1:136
	ds_read2_b64 v[76:79], v76 offset0:120 offset1:192
	v_add_u32_e32 v80, 0xc000, v137
	v_add_u32_e32 v2, 0x9400, v2
	ds_read2_b64 v[80:83], v80 offset0:136 offset1:208
	s_waitcnt lgkmcnt(2)
	v_lshlrev_b32_e32 v85, 16, v1
	v_lshlrev_b32_e32 v84, 16, v0
	s_waitcnt lgkmcnt(1)
	v_mov_b32_e32 v86, v76
	v_mov_b32_e32 v87, v78
	v_pk_mul_f32 v[84:85], v[86:87], v[84:85]
	v_and_b32_e32 v1, 0xffff0000, v1
	v_add_f32_e32 v76, 0, v84
	v_add_f32_e32 v86, v76, v85
	ds_read2_b32 v[84:85], v2 offset0:80 offset1:152
	v_and_b32_e32 v0, 0xffff0000, v0
	v_mov_b32_e32 v78, v77
	v_pk_mul_f32 v[0:1], v[78:79], v[0:1]
	s_waitcnt lgkmcnt(1)
	v_mov_b32_e32 v76, v80
	v_add_f32_e32 v0, 0, v0
	v_add_f32_e32 v2, v0, v1
	s_waitcnt lgkmcnt(0)
	v_lshlrev_b32_e32 v1, 16, v85
	v_lshlrev_b32_e32 v0, 16, v84
	v_mov_b32_e32 v77, v82
	v_pk_mul_f32 v[0:1], v[76:77], v[0:1]
	v_and_b32_e32 v77, 0xffff0000, v85
	v_and_b32_e32 v76, 0xffff0000, v84
	v_mov_b32_e32 v82, v81
	v_add_f32_e32 v0, v86, v0
	v_pk_mul_f32 v[76:77], v[82:83], v[76:77]
	v_add_f32_e32 v0, v0, v1
	v_add_f32_e32 v1, v2, v76
	v_add_f32_e32 v1, v1, v77
	ds_read_b128 v[78:81], v151 offset:37376
	ds_read_b128 v[82:85], v151 offset:37504
	ds_read_b128 v[86:89], v151 offset:37664
	ds_read_b128 v[90:93], v151 offset:37952
	v_mul_f32_e32 v2, 0xbfb8aa3b, v0
	ds_read_b128 v[174:177], v151 offset:38240
	v_exp_f32_e32 v2, v2
	v_mul_f32_e32 v76, 0xbfb8aa3b, v1
	v_exp_f32_e32 v77, v76
	s_waitcnt lgkmcnt(4)
	v_lshlrev_b32_e32 v154, 16, v80
	v_and_b32_e32 v155, 0xffff0000, v80
	v_lshlrev_b32_e32 v94, 16, v78
	v_and_b32_e32 v95, 0xffff0000, v78
	v_lshlrev_b32_e32 v106, 16, v79
	v_and_b32_e32 v107, 0xffff0000, v79
	v_lshlrev_b32_e32 v178, 16, v81
	v_and_b32_e32 v179, 0xffff0000, v81
	ds_read_b128 v[78:81], v151 offset:37792
	s_waitcnt lgkmcnt(3)
	v_lshlrev_b32_e32 v180, 16, v86
	v_and_b32_e32 v181, 0xffff0000, v86
	v_lshlrev_b32_e32 v182, 16, v87
	v_and_b32_e32 v183, 0xffff0000, v87
	v_lshlrev_b32_e32 v184, 16, v88
	v_and_b32_e32 v185, 0xffff0000, v88
	v_lshlrev_b32_e32 v186, 16, v89
	v_and_b32_e32 v187, 0xffff0000, v89
	ds_read_b128 v[86:89], v151 offset:38080
	s_waitcnt lgkmcnt(3)
	v_lshlrev_b32_e32 v188, 16, v90
	v_and_b32_e32 v189, 0xffff0000, v90
	v_lshlrev_b32_e32 v190, 16, v91
	v_and_b32_e32 v191, 0xffff0000, v91
	v_lshlrev_b32_e32 v192, 16, v92
	v_and_b32_e32 v193, 0xffff0000, v92
	v_lshlrev_b32_e32 v194, 16, v93
	v_and_b32_e32 v195, 0xffff0000, v93
	ds_read_b128 v[90:93], v151 offset:38368
	s_waitcnt vmcnt(15)
	v_pk_fma_f32 v[154:155], v[4:5], v[154:155], 0 op_sel_hi:[1,1,0]
	v_add_f32_e32 v2, 1.0, v2
	s_waitcnt vmcnt(13)
	v_pk_fma_f32 v[154:155], v[12:13], v[184:185], v[154:155]
	s_waitcnt lgkmcnt(3)
	v_lshlrev_b32_e32 v198, 16, v176
	v_and_b32_e32 v199, 0xffff0000, v176
	s_waitcnt vmcnt(11)
	v_pk_fma_f32 v[154:155], v[20:21], v[192:193], v[154:155]
	v_rcp_f32_e32 v76, v2
	v_add_f32_e32 v2, 1.0, v77
	s_waitcnt vmcnt(9)
	v_pk_fma_f32 v[154:155], v[28:29], v[198:199], v[154:155]
	v_rcp_f32_e32 v77, v2
	v_mul_f32_e32 v2, 0xbfb8aa3b, v154
	v_lshlrev_b32_e32 v202, 16, v84
	v_and_b32_e32 v203, 0xffff0000, v84
	s_waitcnt lgkmcnt(0)
	v_lshlrev_b32_e32 v214, 16, v92
	v_and_b32_e32 v215, 0xffff0000, v92
	v_exp_f32_e32 v2, v2
	v_mul_f32_e32 v92, 0xbfb8aa3b, v155
	v_lshlrev_b32_e32 v206, 16, v80
	v_and_b32_e32 v207, 0xffff0000, v80
	v_exp_f32_e32 v158, v92
	s_waitcnt vmcnt(7)
	v_pk_fma_f32 v[192:193], v[36:37], v[202:203], 0 op_sel_hi:[1,1,0]
	v_lshlrev_b32_e32 v210, 16, v88
	v_and_b32_e32 v211, 0xffff0000, v88
	s_waitcnt vmcnt(5)
	v_pk_fma_f32 v[192:193], v[44:45], v[206:207], v[192:193]
	v_add_f32_e32 v2, 1.0, v2
	s_waitcnt vmcnt(3)
	v_pk_fma_f32 v[192:193], v[52:53], v[210:211], v[192:193]
	v_rcp_f32_e32 v184, v2
	s_waitcnt vmcnt(1)
; __device__ __forceinline__ float bflo(unsigned u) { return __uint_as_float(u << 16); }
; __device__ __forceinline__ float bfhi(unsigned u) { return __uint_as_float(u & 0xffff0000u); }
; __device__ __forceinline__ float siluf_(float x) { return x * __builtin_amdgcn_rcpf(1.0f + __expf(-x)); }
; template <int N, int RS>
; __device__ __forceinline__ void convN(const bf16_t* rawb, const float (&w)[4][N], int tt, int off, float (&x)[N]) {
; #pragma unroll
;   for (int i = 0; i < N; ++i) x[i] = 0.f;
; #pragma unroll
;   for (int j = 0; j < 4; ++j) {
;     float xv[N];
;     if (N == 8) { const uint4 rv = *(const uint4*)(rawb + (tt + j) * RS + off); unpack8(rv, xv); }
;     else if (N == 4) { const uint2 rv = *(const uint2*)(rawb + (tt + j) * RS + off); xv[0] = bflo(rv.x); xv[1] = bfhi(rv.x); xv[2 % N] = bflo(rv.y); xv[3 % N] = bfhi(rv.y); }
;     else { const unsigned rv = *(const unsigned*)(rawb + (tt + j) * RS + off); xv[0] = bflo(rv); xv[1] = bfhi(rv); }
; #pragma unroll
;     for (int i = 0; i < N; ++i) x[i] += w[j][i] * xv[i];
;   }
;   if (N == 2) {
; #pragma unroll
;     for (int i = 0; i < N; ++i) asm volatile("" : "+v"(x[i]));
;   }
; #pragma unroll
;   for (int i = 0; i < N; ++i) x[i] = siluf_(x[i]);
; }
	v_pk_fma_f32 v[192:193], v[60:61], v[214:215], v[192:193]
	v_add_f32_e32 v2, 1.0, v158
	v_mul_f32_e32 v158, 0xbfb8aa3b, v192
	v_exp_f32_e32 v158, v158
	v_mul_f32_e32 v159, 0xbfb8aa3b, v193
	v_exp_f32_e32 v159, v159
	v_pk_fma_f32 v[178:179], v[6:7], v[178:179], 0 op_sel_hi:[1,1,0]
	v_lshlrev_b32_e32 v176, 16, v177
	v_pk_fma_f32 v[178:179], v[14:15], v[186:187], v[178:179]
	v_and_b32_e32 v177, 0xffff0000, v177
	v_rcp_f32_e32 v185, v2
	v_add_f32_e32 v2, 1.0, v158
	v_pk_fma_f32 v[178:179], v[22:23], v[194:195], v[178:179]
	v_rcp_f32_e32 v198, v2
	v_add_f32_e32 v2, 1.0, v159
	v_pk_fma_f32 v[176:177], v[30:31], v[176:177], v[178:179]
	v_rcp_f32_e32 v199, v2
	v_mul_f32_e32 v2, 0xbfb8aa3b, v176
	v_exp_f32_e32 v2, v2
	v_mul_f32_e32 v158, 0xbfb8aa3b, v177
	v_exp_f32_e32 v158, v158
	v_pk_fma_f32 v[94:95], v[8:9], v[94:95], 0 op_sel_hi:[1,1,0]
	v_lshlrev_b32_e32 v196, 16, v174
	v_pk_fma_f32 v[94:95], v[16:17], v[180:181], v[94:95]
	v_and_b32_e32 v197, 0xffff0000, v174
	v_add_f32_e32 v2, 1.0, v2
	v_pk_fma_f32 v[94:95], v[24:25], v[188:189], v[94:95]
	v_rcp_f32_e32 v186, v2
	v_add_f32_e32 v2, 1.0, v158
	v_pk_fma_f32 v[94:95], v[32:33], v[196:197], v[94:95]
	v_rcp_f32_e32 v187, v2
	v_mul_f32_e32 v2, 0xbfb8aa3b, v94
	v_exp_f32_e32 v2, v2
	v_mul_f32_e32 v158, 0xbfb8aa3b, v95
	v_exp_f32_e32 v158, v158
	v_pk_fma_f32 v[106:107], v[10:11], v[106:107], 0 op_sel_hi:[1,1,0]
	v_lshlrev_b32_e32 v174, 16, v175
	v_pk_fma_f32 v[106:107], v[18:19], v[182:183], v[106:107]
	v_and_b32_e32 v175, 0xffff0000, v175
	v_pk_fma_f32 v[106:107], v[26:27], v[190:191], v[106:107]
	v_add_f32_e32 v2, 1.0, v2
	v_pk_fma_f32 v[106:107], v[34:35], v[174:175], v[106:107]
	v_rcp_f32_e32 v180, v2
	v_add_f32_e32 v2, 1.0, v158
	v_mul_f32_e32 v158, 0xbfb8aa3b, v106
	v_exp_f32_e32 v158, v158
	v_mul_f32_e32 v159, 0xbfb8aa3b, v107
	v_lshlrev_b32_e32 v84, 16, v85
	v_and_b32_e32 v85, 0xffff0000, v85
	v_exp_f32_e32 v159, v159
	v_lshlrev_b32_e32 v80, 16, v81
	v_and_b32_e32 v81, 0xffff0000, v81
	v_pk_fma_f32 v[84:85], v[38:39], v[84:85], 0 op_sel_hi:[1,1,0]
	v_lshlrev_b32_e32 v88, 16, v89
	v_and_b32_e32 v89, 0xffff0000, v89
	v_pk_fma_f32 v[80:81], v[46:47], v[80:81], v[84:85]
	v_lshlrev_b32_e32 v92, 16, v93
	v_and_b32_e32 v93, 0xffff0000, v93
	v_rcp_f32_e32 v181, v2
	v_add_f32_e32 v2, 1.0, v158
	v_pk_fma_f32 v[80:81], v[54:55], v[88:89], v[80:81]
	v_rcp_f32_e32 v174, v2
	v_add_f32_e32 v2, 1.0, v159
	v_pk_fma_f32 v[80:81], v[62:63], v[92:93], v[80:81]
	v_rcp_f32_e32 v175, v2
	v_mul_f32_e32 v2, 0xbfb8aa3b, v80
	v_exp_f32_e32 v2, v2
	v_mul_f32_e32 v84, 0xbfb8aa3b, v81
	v_exp_f32_e32 v89, v84
	v_lshlrev_b32_e32 v200, 16, v82
	v_and_b32_e32 v201, 0xffff0000, v82
	v_lshlrev_b32_e32 v204, 16, v78
	v_and_b32_e32 v205, 0xffff0000, v78
	v_add_f32_e32 v2, 1.0, v2
	v_pk_fma_f32 v[92:93], v[40:41], v[200:201], 0 op_sel_hi:[1,1,0]
	v_lshlrev_b32_e32 v82, 16, v83
	v_and_b32_e32 v83, 0xffff0000, v83
	v_lshlrev_b32_e32 v208, 16, v86
	v_and_b32_e32 v209, 0xffff0000, v86
	v_rcp_f32_e32 v88, v2
	v_add_f32_e32 v2, 1.0, v89
	v_pk_fma_f32 v[92:93], v[48:49], v[204:205], v[92:93]
	v_lshlrev_b32_e32 v78, 16, v79
	v_and_b32_e32 v79, 0xffff0000, v79
	v_lshlrev_b32_e32 v212, 16, v90
	v_and_b32_e32 v213, 0xffff0000, v90
	v_rcp_f32_e32 v89, v2
	v_pk_fma_f32 v[92:93], v[56:57], v[208:209], v[92:93]
	v_pk_fma_f32 v[82:83], v[42:43], v[82:83], 0 op_sel_hi:[1,1,0]
	v_lshlrev_b32_e32 v86, 16, v87
	v_and_b32_e32 v87, 0xffff0000, v87
	s_waitcnt vmcnt(0)
;   __device__ __forceinline__ unsigned char* W() const { return (unsigned char*)(GAS unsigned char*)ws; }
; __device__ __forceinline__ float bflo(unsigned u) { return __uint_as_float(u << 16); }
; __device__ __forceinline__ float sigmoidf_(float x) { return __builtin_amdgcn_rcpf(1.0f + __expf(-x)); }
; __device__ __forceinline__ float softplusf_(float x) { return fmaxf(x, 0.f) + __logf(1.0f + __expf(-fabsf(x))); }
; __device__ __forceinline__ float red8d(float x) { x += dpp_x1(x); x += dpp_x2(x); x += dpp_hm(x); return x; }
; template <int MIX>
; __device__ __forceinline__ void scan_part(const Params& p, const int layer, const int smp, const int b0, const int bstep, const int bend, const int h, const int part, char* lds, const int tid) {
;     ...
; #pragma unroll
;         for (int i = 0; i < VN; ++i) dst[192 + sub * VN + i] = xv[i];
;         float ssq = 0.f, ssk = 0.f;
; #pragma unroll
;         for (int i = 0; i < 8; ++i) { ssq += xq[i] * xq[i]; ssk += xk[i] * xk[i]; }
;         ssq = red8d(ssq); ssk = red8d(ssk);
;         const float rq = rsqrtf(ssq + 1e-6f) * 0.125f, rk = rsqrtf(ssk + 1e-6f);
;         float qk = 0.f;
; #pragma unroll
;         for (int i = 0; i < 8; ++i) { xq[i] *= rq; xk[i] *= rk; qk += xq[i] * xk[i]; }
;         qk = red8d(qk);
;         *(f32x4*)(dst + sub * 8) = (f32x4){xq[0], xq[1], xq[2], xq[3]}; *(f32x4*)(dst + sub * 8 + 4) = (f32x4){xq[4], xq[5], xq[6], xq[7]};
;         *(f32x4*)(dst + 64 + sub * 8) = (f32x4){xk[0], xk[1], xk[2], xk[3]}; *(f32x4*)(dst + 64 + sub * 8 + 4) = (f32x4){xk[4], xk[5], xk[6], xk[7]};
;         if (sub == 0) {
;           const float be = sigmoidf_(bflo(ex0)), al = bflo(ex1);
;           const float a = __expf(-Aexp * softplusf_(al + dtb));
;           *(f32x4*)(scal + tt * 4) = (f32x4){a, be, qk, 0.f};
;         }
;     ...
;     if (MIX == 0 && t0 + 32 < T) {
;       if (tid < 3 * RS / 8) { const uint4 v = *(const uint4*)(rawb + 32 * RS + tid * 8); *(uint4*)(rawb + tid * 8) = v; }
;     }
;     if (t0 + 32 < T) load_chunk_fn<MIX, VN>(p.W(), Pb, t0 + 32 + tt, T, h, vcol, sub, posb, R0, R1, R2, R4, R5, ex0, ex1);
;     {
;       StepIn<MIX, KPL> sa, sb;
;       float osave = 0.f;
;       load_step<MIX, KPL>(qkdv, scal, 0, kg, col, sa);
	v_pk_fma_f32 v[92:93], v[64:65], v[212:213], v[92:93]
	v_pk_fma_f32 v[78:79], v[50:51], v[78:79], v[82:83]
	v_lshlrev_b32_e32 v90, 16, v91
	v_and_b32_e32 v91, 0xffff0000, v91
	v_mul_f32_e32 v2, 0xbfb8aa3b, v92
	v_pk_fma_f32 v[78:79], v[58:59], v[86:87], v[78:79]
	v_exp_f32_e32 v2, v2
	v_mul_f32_e32 v158, 0xbfb8aa3b, v93
	v_pk_fma_f32 v[78:79], v[66:67], v[90:91], v[78:79]
	v_pk_mul_f32 v[106:107], v[106:107], v[174:175]
	v_exp_f32_e32 v158, v158
	v_pk_mul_f32 v[174:175], v[80:81], v[88:89]
	v_mul_f32_e32 v81, 0xbfb8aa3b, v78
	v_exp_f32_e32 v82, v81
	v_mul_f32_e32 v81, 0xbfb8aa3b, v79
	v_exp_f32_e32 v83, v81
	v_add_f32_e32 v2, 1.0, v2
	v_rcp_f32_e32 v80, v2
	v_add_f32_e32 v2, 1.0, v158
	v_rcp_f32_e32 v81, v2
	v_add_f32_e32 v2, 1.0, v82
	v_rcp_f32_e32 v82, v2
	v_add_f32_e32 v2, 1.0, v83
	v_rcp_f32_e32 v83, v2
	v_pk_mul_f32 v[94:95], v[94:95], v[180:181]
	v_pk_mul_f32 v[88:89], v[92:93], v[80:81]
	v_pk_mul_f32 v[180:181], v[94:95], v[94:95]
	v_pk_mul_f32 v[80:81], v[88:89], v[88:89]
	v_pk_mul_f32 v[90:91], v[78:79], v[82:83]
	v_pk_mul_f32 v[84:85], v[106:107], v[106:107]
	v_pk_mul_f32 v[78:79], v[90:91], v[90:91]
	v_mov_b32_e32 v82, v80
	v_mov_b32_e32 v83, v180
	v_mov_b32_e32 v180, v81
	v_pk_mul_f32 v[154:155], v[154:155], v[184:185]
	v_pk_mul_f32 v[192:193], v[192:193], v[198:199]
	v_pk_add_f32 v[80:81], v[82:83], v[180:181]
	v_mov_b32_e32 v82, v78
	v_mov_b32_e32 v83, v84
	v_pk_mul_f32 v[184:185], v[154:155], v[154:155]
	v_pk_mul_f32 v[178:179], v[192:193], v[192:193]
	v_pk_add_f32 v[80:81], v[80:81], v[82:83]
	v_mov_b32_e32 v84, v79
	v_pk_mul_f32 v[176:177], v[176:177], v[186:187]
	v_pk_add_f32 v[78:79], v[84:85], v[80:81]
	v_mov_b32_e32 v80, v178
	v_mov_b32_e32 v81, v184
	v_pk_mul_f32 v[182:183], v[176:177], v[176:177]
	v_pk_mul_f32 v[86:87], v[174:175], v[174:175]
	v_pk_add_f32 v[78:79], v[80:81], v[78:79]
	v_mov_b32_e32 v184, v179
	v_pk_add_f32 v[78:79], v[184:185], v[78:79]
	v_mov_b32_e32 v80, v86
	v_mov_b32_e32 v81, v182
	v_pk_add_f32 v[78:79], v[80:81], v[78:79]
	v_mov_b32_e32 v182, v87
	v_pk_add_f32 v[78:79], v[182:183], v[78:79]
	s_mov_b32 s44, 0x358637bd
	v_pk_mul_f32 v[0:1], v[0:1], v[76:77]
	v_mov_b32_dpp v81, v79 quad_perm:[1,0,3,2] row_mask:0xf bank_mask:0xf bound_ctrl:1
	v_mov_b32_dpp v80, v78 quad_perm:[1,0,3,2] row_mask:0xf bank_mask:0xf bound_ctrl:1
	v_pk_add_f32 v[78:79], v[78:79], v[80:81]
	ds_write_b64 v141, v[0:1] offset:768
	s_nop 0
	v_mov_b32_dpp v81, v79 quad_perm:[2,3,0,1] row_mask:0xf bank_mask:0xf bound_ctrl:1
	v_mov_b32_dpp v80, v78 quad_perm:[2,3,0,1] row_mask:0xf bank_mask:0xf bound_ctrl:1
	v_pk_add_f32 v[78:79], v[78:79], v[80:81]
	s_nop 1
	v_mov_b32_dpp v81, v79 row_half_mirror row_mask:0xf bank_mask:0xf bound_ctrl:1
	v_mov_b32_dpp v80, v78 row_half_mirror row_mask:0xf bank_mask:0xf bound_ctrl:1
	v_pk_add_f32 v[78:79], v[78:79], v[80:81]
	s_nop 0
	v_pk_add_f32 v[78:79], v[78:79], s[44:45] op_sel_hi:[1,0]
	s_nop 0
	v_mul_f32_e32 v2, 0x4b800000, v79
	v_cmp_gt_f32_e32 vcc, s92, v79
	s_nop 1
	v_cndmask_b32_e32 v2, v79, v2, vcc
	v_rsq_f32_e32 v2, v2
	s_nop 0
	v_mul_f32_e32 v0, 0x45800000, v2
	v_cndmask_b32_e32 v0, v2, v0, vcc
	v_mul_f32_e32 v0, 0x3e000000, v0
	v_pk_mul_f32 v[76:77], v[94:95], v[0:1] op_sel_hi:[1,0]
	v_mul_f32_e32 v1, 0x4b800000, v78
	v_cmp_gt_f32_e32 vcc, s92, v78
	s_nop 1
	v_cndmask_b32_e32 v1, v78, v1, vcc
	v_rsq_f32_e32 v1, v1
	s_nop 0
	v_pk_mul_f32 v[78:79], v[106:107], v[0:1] op_sel_hi:[1,0]
	v_pk_mul_f32 v[80:81], v[154:155], v[0:1] op_sel_hi:[1,0]
	v_pk_mul_f32 v[82:83], v[176:177], v[0:1] op_sel_hi:[1,0]
	v_mul_f32_e32 v0, 0x45800000, v1
	v_cndmask_b32_e32 v0, v1, v0, vcc
	v_pk_mul_f32 v[84:85], v[88:89], v[0:1] op_sel_hi:[1,0]
	s_nop 0
	v_pk_mul_f32 v[86:87], v[90:91], v[0:1] op_sel_hi:[1,0]
	s_nop 0
	v_pk_mul_f32 v[88:89], v[192:193], v[0:1] op_sel_hi:[1,0]
	s_nop 0
	v_pk_mul_f32 v[90:91], v[174:175], v[0:1] op_sel_hi:[1,0]
	ds_write_b128 v152, v[76:79]
	ds_write_b128 v152, v[80:83] offset:16
	ds_write_b128 v152, v[84:87] offset:256
	ds_write_b128 v152, v[88:91] offset:272
	s_and_b64 exec, exec, s[38:39]
	s_cbranch_execz .LBB0_426
	v_mov_b32_e32 v2, 0
	v_lshlrev_b32_e32 v0, 16, v133
	v_mul_f32_e32 v0, 0xbfb8aa3b, v0
	v_exp_f32_e32 v0, v0
	s_mov_b32 s27, 0xbfb8aa3b
	v_add_f32_e32 v0, 1.0, v0
	v_rcp_f32_e32 v1, v0
	v_lshlrev_b32_e32 v0, 16, v99
	v_add_f32_e32 v0, v132, v0
	v_max_f32_e32 v76, 0, v0
	v_mul_f32_e64 v0, |v0|, s27
	v_exp_f32_e32 v0, v0
	s_mov_b32 s27, 0x3f317217
	v_add_f32_e32 v0, 1.0, v0
	v_cmp_gt_f32_e32 vcc, s92, v0
	s_nop 1
	v_cndmask_b32_e64 v77, 0, 32, vcc
	v_ldexp_f32 v0, v0, v77
	v_log_f32_e32 v0, v0
	s_nop 0
	v_mul_f32_e32 v77, 0x3f317217, v0
	v_fma_f32 v77, v0, s27, -v77
	v_fmac_f32_e32 v77, 0x3377d1cf, v0
	s_mov_b32 s27, 0x7f800000
	v_fmac_f32_e32 v77, 0x3f317217, v0
	v_cmp_lt_f32_e64 s[44:45], |v0|, s27
	s_nop 1
	v_cndmask_b32_e64 v0, v0, v77, s[44:45]
	v_cndmask_b32_e32 v77, 0, v163, vcc
	v_sub_f32_e32 v0, v0, v77
	v_add_f32_e32 v0, v76, v0
	v_mul_f32_e32 v0, v0, v146
	v_mul_f32_e32 v0, 0xbfb8aa3b, v0
	v_exp_f32_e32 v0, v0
	ds_write_b128 v142, v[0:3] offset:36864
.LBB0_426:
	s_or_b64 exec, exec, s[50:51]
	s_cmpk_lt_u32 s23, 0x7f0
	s_cselect_b64 s[50:51], -1, 0
	s_cmpk_gt_u32 s23, 0x7ef
	s_cselect_b64 s[44:45], -1, 0
	s_and_b64 s[56:57], s[40:41], s[50:51]
	s_waitcnt lgkmcnt(0)
	s_barrier
	v_mov_b32_e32 v211, v145
	v_mov_b32_e32 v212, v136
	v_mov_b32_e32 v213, 0
	v_and_b32_e32 v214, 12, v135
	v_lshl_add_u32 v214, v214, 6, v136
	ds_read_b128 v[92:95], v211 offset:256
	ds_read_b64 v[106:107], v213 offset:36864
	ds_read_b32 v182, v212 offset:768
	ds_read_b128 v[76:79], v211
	ds_read_b128 v[174:177], v211 offset:1280
	ds_read_b64 v[154:155], v213 offset:36880
	ds_read_b32 v188, v212 offset:1792
	ds_read_b128 v[80:83], v211 offset:1024
	s_andn2_b64 vcc, exec, s[50:51]
	s_add_i32 s27, s23, 32
	s_cbranch_vccnz .LBB0_432
	v_add_u32_e32 v0, s27, v131
	s_movk_i32 s29, 0x810
	v_cmp_gt_i32_e32 vcc, s29, v0
	s_and_saveexec_b64 s[50:51], vcc
	s_cbranch_execz .LBB0_431
	s_waitcnt vmcnt(3)
	v_mov_b64_e32 v[68:69], s[2:3]
	v_mad_i64_i32 v[0:1], s[52:53], v0, s68, v[68:69]
	v_lshl_add_u64 v[68:69], s[34:35], 1, v[0:1]
	v_mov_b32_e32 v97, v3
	s_waitcnt vmcnt(0)
	v_mov_b32_e32 v99, v3
	v_readlane_b32 s52, v254, 17
	v_lshl_add_u64 v[70:71], v[68:69], 0, v[96:97]
	v_lshl_add_u64 v[72:73], v[68:69], 0, v[98:99]
	v_readlane_b32 s53, v254, 18
	s_lshl_b32 s52, s46, 1
	global_load_dword v97, v[70:71], off offset:1024
	s_nop 0
	global_load_dwordx4 v[68:71], v[72:73], off
	v_lshl_add_u64 v[0:1], v[0:1], 0, s[52:53]
	global_load_dwordx4 v[72:75], v[72:73], off offset:512
	s_nop 0
	global_load_ushort v133, v[0:1], off offset:1536
	global_load_ushort v99, v[0:1], off offset:1544
	s_mov_b32 s29, s53
	v_writelane_b32 v254, s28, 17
	s_nop 1
	v_writelane_b32 v254, s29, 18

; template <int KG> __device__ __forceinline__ float redKG(float x) { x = red8d(x); if (KG == 16) x += dpp_rm(x); return x; }
; template <int MIX, int KPL, int KG>
; __device__ __forceinline__ float do_step(const StepIn<MIX, KPL>& s, float (&S)[KPL], const float gam) {
;   if (MIX == 0) {
;     float kS0 = 0.f, kS1 = 0.f, qS0 = 0.f, qS1 = 0.f;
; #pragma unroll
;     for (int i = 0; i < KPL; i += 2) { kS0 += s.k[i] * S[i]; kS1 += s.k[i + 1] * S[i + 1]; qS0 += s.q[i] * S[i]; qS1 += s.q[i + 1] * S[i + 1]; }
;     const float kS = redKG<KG>(kS0 + kS1), qS = redKG<KG>(qS0 + qS1);
;     const float w = s.be * (s.v - s.a * kS);
; #pragma unroll
;     for (int i = 0; i < KPL; ++i) S[i] = s.a * S[i] + s.k[i] * w;
;     return s.a * qS + s.qk * w;
; template <int MIX>
; __device__ __forceinline__ void scan_part(const Params& p, const int layer, const int smp, const int b0, const int bstep, const int bend, const int h, const int part, char* lds, const int tid) {
;     ...
;       for (int t = 0; t < ntok; t += 2) {
;         load_step<MIX, KPL>(qkdv, scal, t + 1, kg, col, sb);
;         __builtin_amdgcn_sched_barrier(0);
;         const float oa = do_step<MIX, KPL, KG>(sa, S, gam);
;         osave = (kg == (t & (KG - 1))) ? oa : osave;
;         load_step<MIX, KPL>(qkdv, scal, min(t + 2, ntok - 1), kg, col, sa);
;         __builtin_amdgcn_sched_barrier(0);
;         const float ob = do_step<MIX, KPL, KG>(sb, S, gam);
;         osave = (kg == ((t + 1) & (KG - 1))) ? ob : osave;
;         if (((t + 2) & (KG - 1)) == 0) obuf[(t + 2 - KG + kg) * CW + col] = osave;
;       }
.LBB0_432:
	s_lshr_b32 s50, s26, 4
.Lscan0p_blk:
	s_waitcnt lgkmcnt(4)
	v_pk_mul_f32 v[192:193], v[92:93], v[104:105]
	v_pk_fma_f32 v[192:193], v[94:95], v[102:103], v[192:193]
	v_add_f32_e32 v203, v192, v193
	v_pk_mul_f32 v[194:195], v[104:105], v[106:107] op_sel_hi:[1,0]
	v_pk_mul_f32 v[196:197], v[102:103], v[106:107] op_sel_hi:[1,0]
	v_add_f32_dpp v203, v203, v203 quad_perm:[1,0,3,2] row_mask:0xf bank_mask:0xf bound_ctrl:1
	ds_read_b128 v[178:181], v211 offset:2304
	ds_read_b64 v[158:159], v213 offset:36896
	v_add_f32_dpp v203, v203, v203 quad_perm:[2,3,0,1] row_mask:0xf bank_mask:0xf bound_ctrl:1
	ds_read_b32 v189, v212 offset:2816
	ds_read_b128 v[184:187], v211 offset:3328
	v_add_f32_dpp v203, v203, v203 row_half_mirror row_mask:0xf bank_mask:0xf bound_ctrl:1
	ds_read_b64 v[168:169], v213 offset:36912
	ds_read_b32 v190, v212 offset:3840
	v_add_f32_dpp v203, v203, v203 row_mirror row_mask:0xf bank_mask:0xf bound_ctrl:1
	v_fma_f32 v204, -v106, v203, v182
	v_mul_f32_e32 v206, v107, v204
	v_pk_fma_f32 v[104:105], v[92:93], v[206:207], v[194:195] op_sel_hi:[1,0,1]
	v_pk_fma_f32 v[102:103], v[94:95], v[206:207], v[196:197] op_sel_hi:[1,0,1]
	s_waitcnt lgkmcnt(4)
	v_pk_mul_f32 v[192:193], v[174:175], v[104:105]
	v_pk_fma_f32 v[192:193], v[176:177], v[102:103], v[192:193]
	v_add_f32_e32 v203, v192, v193
	v_pk_mul_f32 v[198:199], v[76:77], v[104:105]
	v_pk_mul_f32 v[194:195], v[104:105], v[154:155] op_sel_hi:[1,0]
	v_add_f32_dpp v203, v203, v203 quad_perm:[1,0,3,2] row_mask:0xf bank_mask:0xf bound_ctrl:1
	v_pk_fma_f32 v[198:199], v[78:79], v[102:103], v[198:199]
	v_pk_mul_f32 v[196:197], v[102:103], v[154:155] op_sel_hi:[1,0]
	v_add_f32_dpp v203, v203, v203 quad_perm:[2,3,0,1] row_mask:0xf bank_mask:0xf bound_ctrl:1
	ds_read_b128 v[84:87], v211 offset:2048
	ds_read_b128 v[92:95], v211 offset:4352
	v_add_f32_dpp v203, v203, v203 row_half_mirror row_mask:0xf bank_mask:0xf bound_ctrl:1
	v_add_f32_e32 v191, v198, v199
	ds_read_b64 v[106:107], v213 offset:36928
	v_add_f32_dpp v203, v203, v203 row_mirror row_mask:0xf bank_mask:0xf bound_ctrl:1
	v_fma_f32 v204, -v154, v203, v188
	v_mul_f32_e32 v206, v155, v204
	v_pk_fma_f32 v[104:105], v[174:175], v[206:207], v[194:195] op_sel_hi:[1,0,1]
	v_pk_fma_f32 v[102:103], v[176:177], v[206:207], v[196:197] op_sel_hi:[1,0,1]
	v_pk_mul_f32 v[192:193], v[178:179], v[104:105]
	v_pk_fma_f32 v[192:193], v[180:181], v[102:103], v[192:193]
	v_add_f32_e32 v203, v192, v193
	v_pk_mul_f32 v[200:201], v[80:81], v[104:105]
	v_pk_mul_f32 v[194:195], v[104:105], v[158:159] op_sel_hi:[1,0]
	v_add_f32_dpp v203, v203, v203 quad_perm:[1,0,3,2] row_mask:0xf bank_mask:0xf bound_ctrl:1
	v_pk_fma_f32 v[200:201], v[82:83], v[102:103], v[200:201]
	v_pk_mul_f32 v[196:197], v[102:103], v[158:159] op_sel_hi:[1,0]
	v_add_f32_dpp v203, v203, v203 quad_perm:[2,3,0,1] row_mask:0xf bank_mask:0xf bound_ctrl:1
	ds_read_b32 v182, v212 offset:4864
	ds_read_b128 v[88:91], v211 offset:3072
	v_add_f32_dpp v203, v203, v203 row_half_mirror row_mask:0xf bank_mask:0xf bound_ctrl:1
	ds_read_b128 v[174:177], v211 offset:5376
	v_add_f32_e32 v202, v200, v201
	v_add_f32_dpp v203, v203, v203 row_mirror row_mask:0xf bank_mask:0xf bound_ctrl:1
	s_waitcnt lgkmcnt(3)
	v_fma_f32 v204, -v158, v203, v189
	v_mul_f32_e32 v206, v159, v204
	v_pk_fma_f32 v[104:105], v[178:179], v[206:207], v[194:195] op_sel_hi:[1,0,1]
	v_pk_fma_f32 v[102:103], v[180:181], v[206:207], v[196:197] op_sel_hi:[1,0,1]
	v_pk_mul_f32 v[192:193], v[184:185], v[104:105]
	v_pk_fma_f32 v[192:193], v[186:187], v[102:103], v[192:193]
	v_add_f32_e32 v203, v192, v193
	v_pk_mul_f32 v[198:199], v[84:85], v[104:105]
	v_pk_mul_f32 v[194:195], v[104:105], v[168:169] op_sel_hi:[1,0]
	v_add_f32_dpp v203, v203, v203 quad_perm:[1,0,3,2] row_mask:0xf bank_mask:0xf bound_ctrl:1
	v_pk_fma_f32 v[198:199], v[86:87], v[102:103], v[198:199]
	v_pk_mul_f32 v[196:197], v[102:103], v[168:169] op_sel_hi:[1,0]
	v_add_f32_dpp v203, v203, v203 quad_perm:[2,3,0,1] row_mask:0xf bank_mask:0xf bound_ctrl:1
	ds_read_b64 v[154:155], v213 offset:36944
	ds_read_b32 v188, v212 offset:5888
	v_add_f32_dpp v203, v203, v203 row_half_mirror row_mask:0xf bank_mask:0xf bound_ctrl:1
	ds_read_b128 v[76:79], v211 offset:4096
	ds_read_b128 v[178:181], v211 offset:6400
	v_add_f32_dpp v203, v203, v203 row_mirror row_mask:0xf bank_mask:0xf bound_ctrl:1
	v_fma_f32 v204, -v168, v203, v190
	v_mul_f32_e32 v206, v169, v204
	v_pk_fma_f32 v[104:105], v[184:185], v[206:207], v[194:195] op_sel_hi:[1,0,1]
	v_pk_fma_f32 v[102:103], v[186:187], v[206:207], v[196:197] op_sel_hi:[1,0,1]
	v_pk_mul_f32 v[192:193], v[92:93], v[104:105]
	v_pk_fma_f32 v[192:193], v[94:95], v[102:103], v[192:193]
	v_add_f32_e32 v203, v192, v193
	s_waitcnt lgkmcnt(2)
	v_pk_mul_f32 v[200:201], v[88:89], v[104:105]
	v_pk_mul_f32 v[194:195], v[104:105], v[106:107] op_sel_hi:[1,0]
	v_add_f32_dpp v203, v203, v203 quad_perm:[1,0,3,2] row_mask:0xf bank_mask:0xf bound_ctrl:1
	v_pk_fma_f32 v[200:201], v[90:91], v[102:103], v[200:201]
	v_pk_mul_f32 v[196:197], v[102:103], v[106:107] op_sel_hi:[1,0]
	v_add_f32_dpp v203, v203, v203 quad_perm:[2,3,0,1] row_mask:0xf bank_mask:0xf bound_ctrl:1
	v_add_f32_dpp v191, v191, v191 quad_perm:[1,0,3,2] row_mask:0xf bank_mask:0xf bound_ctrl:1
	ds_read_b64 v[158:159], v213 offset:36960
	v_add_f32_dpp v203, v203, v203 row_half_mirror row_mask:0xf bank_mask:0xf bound_ctrl:1
	v_add_f32_dpp v191, v191, v191 quad_perm:[2,3,0,1] row_mask:0xf bank_mask:0xf bound_ctrl:1
	ds_read_b32 v189, v212 offset:6912
	v_add_f32_dpp v203, v203, v203 row_mirror row_mask:0xf bank_mask:0xf bound_ctrl:1
	v_fma_f32 v204, -v106, v203, v182
	v_mul_f32_e32 v206, v107, v204
	v_pk_fma_f32 v[104:105], v[92:93], v[206:207], v[194:195] op_sel_hi:[1,0,1]
	v_pk_fma_f32 v[102:103], v[94:95], v[206:207], v[196:197] op_sel_hi:[1,0,1]
	v_pk_mul_f32 v[192:193], v[174:175], v[104:105]
	v_pk_fma_f32 v[192:193], v[176:177], v[102:103], v[192:193]
	v_add_f32_e32 v203, v192, v193
	v_add_f32_dpp v191, v191, v191 row_half_mirror row_mask:0xf bank_mask:0xf bound_ctrl:1
	v_pk_mul_f32 v[194:195], v[104:105], v[154:155] op_sel_hi:[1,0]
	v_add_f32_dpp v203, v203, v203 quad_perm:[1,0,3,2] row_mask:0xf bank_mask:0xf bound_ctrl:1
	v_add_f32_dpp v205, v191, v191 row_mirror row_mask:0xf bank_mask:0x1
	v_add_f32_e32 v191, v198, v199
	v_add_f32_dpp v203, v203, v203 quad_perm:[2,3,0,1] row_mask:0xf bank_mask:0xf bound_ctrl:1
	s_waitcnt lgkmcnt(0)
; template <int KG> __device__ __forceinline__ float redKG(float x) { x = red8d(x); if (KG == 16) x += dpp_rm(x); return x; }
; template <int MIX, int KPL, int KG>
; __device__ __forceinline__ float do_step(const StepIn<MIX, KPL>& s, float (&S)[KPL], const float gam) {
;   if (MIX == 0) {
;     float kS0 = 0.f, kS1 = 0.f, qS0 = 0.f, qS1 = 0.f;
; #pragma unroll
;     for (int i = 0; i < KPL; i += 2) { kS0 += s.k[i] * S[i]; kS1 += s.k[i + 1] * S[i + 1]; qS0 += s.q[i] * S[i]; qS1 += s.q[i + 1] * S[i + 1]; }
;     const float kS = redKG<KG>(kS0 + kS1), qS = redKG<KG>(qS0 + qS1);
;     const float w = s.be * (s.v - s.a * kS);
; #pragma unroll
;     for (int i = 0; i < KPL; ++i) S[i] = s.a * S[i] + s.k[i] * w;
;     return s.a * qS + s.qk * w;
; template <int MIX>
; __device__ __forceinline__ void scan_part(const Params& p, const int layer, const int smp, const int b0, const int bstep, const int bend, const int h, const int part, char* lds, const int tid) {
;     ...
;       for (int t = 0; t < ntok; t += 2) {
;         load_step<MIX, KPL>(qkdv, scal, t + 1, kg, col, sb);
;         __builtin_amdgcn_sched_barrier(0);
;         const float oa = do_step<MIX, KPL, KG>(sa, S, gam);
;         osave = (kg == (t & (KG - 1))) ? oa : osave;
;         load_step<MIX, KPL>(qkdv, scal, min(t + 2, ntok - 1), kg, col, sa);
;         __builtin_amdgcn_sched_barrier(0);
;         const float ob = do_step<MIX, KPL, KG>(sb, S, gam);
;         osave = (kg == ((t + 1) & (KG - 1))) ? ob : osave;
;         if (((t + 2) & (KG - 1)) == 0) obuf[(t + 2 - KG + kg) * CW + col] = osave;
;       }
	v_pk_mul_f32 v[198:199], v[76:77], v[104:105]
	v_pk_fma_f32 v[198:199], v[78:79], v[102:103], v[198:199]
	v_add_f32_dpp v203, v203, v203 row_half_mirror row_mask:0xf bank_mask:0xf bound_ctrl:1
	v_pk_mul_f32 v[196:197], v[102:103], v[154:155] op_sel_hi:[1,0]
	ds_read_b128 v[80:83], v211 offset:5120
	v_add_f32_dpp v203, v203, v203 row_mirror row_mask:0xf bank_mask:0xf bound_ctrl:1
	v_fma_f32 v204, -v154, v203, v188
	v_mul_f32_e32 v206, v155, v204
	v_pk_fma_f32 v[104:105], v[174:175], v[206:207], v[194:195] op_sel_hi:[1,0,1]
	v_pk_fma_f32 v[102:103], v[176:177], v[206:207], v[196:197] op_sel_hi:[1,0,1]
	v_pk_mul_f32 v[192:193], v[178:179], v[104:105]
	v_pk_fma_f32 v[192:193], v[180:181], v[102:103], v[192:193]
	v_add_f32_e32 v203, v192, v193
	ds_read_b128 v[184:187], v211 offset:7424
	v_add_f32_dpp v202, v202, v202 quad_perm:[1,0,3,2] row_mask:0xf bank_mask:0xf bound_ctrl:1
	v_add_f32_dpp v203, v203, v203 quad_perm:[1,0,3,2] row_mask:0xf bank_mask:0xf bound_ctrl:1
	v_pk_mul_f32 v[194:195], v[104:105], v[158:159] op_sel_hi:[1,0]
	v_add_f32_dpp v202, v202, v202 quad_perm:[2,3,0,1] row_mask:0xf bank_mask:0xf bound_ctrl:1
	v_add_f32_dpp v203, v203, v203 quad_perm:[2,3,0,1] row_mask:0xf bank_mask:0xf bound_ctrl:1
	v_pk_mul_f32 v[196:197], v[102:103], v[158:159] op_sel_hi:[1,0]
	v_add_f32_dpp v202, v202, v202 row_half_mirror row_mask:0xf bank_mask:0xf bound_ctrl:1
	v_add_f32_dpp v203, v203, v203 row_half_mirror row_mask:0xf bank_mask:0xf bound_ctrl:1
	ds_read_b64 v[168:169], v213 offset:36976
	v_add_f32_dpp v208, v202, v202 row_mirror row_mask:0xf bank_mask:0x1
	v_add_f32_dpp v203, v203, v203 row_mirror row_mask:0xf bank_mask:0xf bound_ctrl:1
	v_add_f32_e32 v202, v200, v201
	v_fma_f32 v204, -v158, v203, v189
	s_waitcnt lgkmcnt(1)
	v_pk_mul_f32 v[200:201], v[80:81], v[104:105]
	v_mul_f32_e32 v206, v159, v204
	v_pk_fma_f32 v[200:201], v[82:83], v[102:103], v[200:201]
	v_pk_fma_f32 v[104:105], v[178:179], v[206:207], v[194:195] op_sel_hi:[1,0,1]
	v_pk_fma_f32 v[102:103], v[180:181], v[206:207], v[196:197] op_sel_hi:[1,0,1]
	v_pk_mul_f32 v[192:193], v[184:185], v[104:105]
	ds_read_b32 v190, v212 offset:7936
	v_pk_fma_f32 v[192:193], v[186:187], v[102:103], v[192:193]
	ds_read_b128 v[84:87], v211 offset:6144
	v_add_f32_e32 v203, v192, v193
	ds_read_b128 v[92:95], v211 offset:8448
	v_add_f32_dpp v191, v191, v191 quad_perm:[1,0,3,2] row_mask:0xf bank_mask:0xf bound_ctrl:1
	v_add_f32_dpp v203, v203, v203 quad_perm:[1,0,3,2] row_mask:0xf bank_mask:0xf bound_ctrl:1
	s_waitcnt lgkmcnt(3)
	v_pk_mul_f32 v[194:195], v[104:105], v[168:169] op_sel_hi:[1,0]
	v_add_f32_dpp v191, v191, v191 quad_perm:[2,3,0,1] row_mask:0xf bank_mask:0xf bound_ctrl:1
	v_add_f32_dpp v203, v203, v203 quad_perm:[2,3,0,1] row_mask:0xf bank_mask:0xf bound_ctrl:1
	v_pk_mul_f32 v[196:197], v[102:103], v[168:169] op_sel_hi:[1,0]
	v_add_f32_dpp v191, v191, v191 row_half_mirror row_mask:0xf bank_mask:0xf bound_ctrl:1
	v_add_f32_dpp v203, v203, v203 row_half_mirror row_mask:0xf bank_mask:0xf bound_ctrl:1
	ds_read_b64 v[106:107], v213 offset:36992
	v_add_f32_dpp v209, v191, v191 row_mirror row_mask:0xf bank_mask:0x1
	v_add_f32_dpp v203, v203, v203 row_mirror row_mask:0xf bank_mask:0xf bound_ctrl:1
	v_add_f32_e32 v191, v198, v199
	s_waitcnt lgkmcnt(1)
	v_fma_f32 v204, -v168, v203, v190
	v_pk_mul_f32 v[198:199], v[84:85], v[104:105]
	v_mul_f32_e32 v206, v169, v204
	v_pk_fma_f32 v[198:199], v[86:87], v[102:103], v[198:199]
	v_pk_fma_f32 v[104:105], v[184:185], v[206:207], v[194:195] op_sel_hi:[1,0,1]
	v_pk_fma_f32 v[102:103], v[186:187], v[206:207], v[196:197] op_sel_hi:[1,0,1]
	v_pk_mul_f32 v[192:193], v[92:93], v[104:105]
	ds_read_b32 v182, v212 offset:8960
	v_pk_fma_f32 v[192:193], v[94:95], v[102:103], v[192:193]
	ds_read_b128 v[88:91], v211 offset:7168
	v_add_f32_e32 v203, v192, v193
	ds_read_b128 v[174:177], v211 offset:9472
	v_add_f32_dpp v202, v202, v202 quad_perm:[1,0,3,2] row_mask:0xf bank_mask:0xf bound_ctrl:1
	v_add_f32_dpp v203, v203, v203 quad_perm:[1,0,3,2] row_mask:0xf bank_mask:0xf bound_ctrl:1
	s_waitcnt lgkmcnt(3)
	v_pk_mul_f32 v[194:195], v[104:105], v[106:107] op_sel_hi:[1,0]
	v_add_f32_dpp v202, v202, v202 quad_perm:[2,3,0,1] row_mask:0xf bank_mask:0xf bound_ctrl:1
	v_add_f32_dpp v203, v203, v203 quad_perm:[2,3,0,1] row_mask:0xf bank_mask:0xf bound_ctrl:1
	v_pk_mul_f32 v[196:197], v[102:103], v[106:107] op_sel_hi:[1,0]
	v_add_f32_dpp v202, v202, v202 row_half_mirror row_mask:0xf bank_mask:0xf bound_ctrl:1
	v_add_f32_dpp v203, v203, v203 row_half_mirror row_mask:0xf bank_mask:0xf bound_ctrl:1
	ds_read_b64 v[154:155], v213 offset:37008
	v_add_f32_dpp v210, v202, v202 row_mirror row_mask:0xf bank_mask:0x1
	v_add_f32_dpp v203, v203, v203 row_mirror row_mask:0xf bank_mask:0xf bound_ctrl:1
	v_add_f32_e32 v202, v200, v201
	s_waitcnt lgkmcnt(1)
	v_fma_f32 v204, -v106, v203, v182
	v_pk_mul_f32 v[200:201], v[88:89], v[104:105]
	v_mul_f32_e32 v206, v107, v204
	v_pk_fma_f32 v[200:201], v[90:91], v[102:103], v[200:201]
	v_pk_fma_f32 v[104:105], v[92:93], v[206:207], v[194:195] op_sel_hi:[1,0,1]
	v_pk_fma_f32 v[102:103], v[94:95], v[206:207], v[196:197] op_sel_hi:[1,0,1]
	v_pk_mul_f32 v[192:193], v[174:175], v[104:105]
	ds_read_b32 v188, v212 offset:9984
	v_pk_fma_f32 v[192:193], v[176:177], v[102:103], v[192:193]
	ds_read_b128 v[76:79], v211 offset:8192
	v_add_f32_e32 v203, v192, v193
	ds_read_b128 v[178:181], v211 offset:10496
	v_add_f32_dpp v191, v191, v191 quad_perm:[1,0,3,2] row_mask:0xf bank_mask:0xf bound_ctrl:1
	v_add_f32_dpp v203, v203, v203 quad_perm:[1,0,3,2] row_mask:0xf bank_mask:0xf bound_ctrl:1
	s_waitcnt lgkmcnt(3)
; template <int KG> __device__ __forceinline__ float redKG(float x) { x = red8d(x); if (KG == 16) x += dpp_rm(x); return x; }
; template <int MIX, int KPL, int KG>
; __device__ __forceinline__ float do_step(const StepIn<MIX, KPL>& s, float (&S)[KPL], const float gam) {
;   if (MIX == 0) {
;     float kS0 = 0.f, kS1 = 0.f, qS0 = 0.f, qS1 = 0.f;
; #pragma unroll
;     for (int i = 0; i < KPL; i += 2) { kS0 += s.k[i] * S[i]; kS1 += s.k[i + 1] * S[i + 1]; qS0 += s.q[i] * S[i]; qS1 += s.q[i + 1] * S[i + 1]; }
;     const float kS = redKG<KG>(kS0 + kS1), qS = redKG<KG>(qS0 + qS1);
;     const float w = s.be * (s.v - s.a * kS);
; #pragma unroll
;     for (int i = 0; i < KPL; ++i) S[i] = s.a * S[i] + s.k[i] * w;
;     return s.a * qS + s.qk * w;
; template <int MIX>
; __device__ __forceinline__ void scan_part(const Params& p, const int layer, const int smp, const int b0, const int bstep, const int bend, const int h, const int part, char* lds, const int tid) {
;     ...
;       for (int t = 0; t < ntok; t += 2) {
;         load_step<MIX, KPL>(qkdv, scal, t + 1, kg, col, sb);
;         __builtin_amdgcn_sched_barrier(0);
;         const float oa = do_step<MIX, KPL, KG>(sa, S, gam);
;         osave = (kg == (t & (KG - 1))) ? oa : osave;
;         load_step<MIX, KPL>(qkdv, scal, min(t + 2, ntok - 1), kg, col, sa);
;         __builtin_amdgcn_sched_barrier(0);
;         const float ob = do_step<MIX, KPL, KG>(sb, S, gam);
;         osave = (kg == ((t + 1) & (KG - 1))) ? ob : osave;
;         if (((t + 2) & (KG - 1)) == 0) obuf[(t + 2 - KG + kg) * CW + col] = osave;
;       }
	v_pk_mul_f32 v[194:195], v[104:105], v[154:155] op_sel_hi:[1,0]
	v_add_f32_dpp v191, v191, v191 quad_perm:[2,3,0,1] row_mask:0xf bank_mask:0xf bound_ctrl:1
	v_add_f32_dpp v203, v203, v203 quad_perm:[2,3,0,1] row_mask:0xf bank_mask:0xf bound_ctrl:1
	v_pk_mul_f32 v[196:197], v[102:103], v[154:155] op_sel_hi:[1,0]
	v_add_f32_dpp v191, v191, v191 row_half_mirror row_mask:0xf bank_mask:0xf bound_ctrl:1
	v_add_f32_dpp v203, v203, v203 row_half_mirror row_mask:0xf bank_mask:0xf bound_ctrl:1
	ds_read_b64 v[158:159], v213 offset:37024
	v_add_f32_dpp v205, v191, v191 row_mirror row_mask:0xf bank_mask:0x2
	v_add_f32_dpp v203, v203, v203 row_mirror row_mask:0xf bank_mask:0xf bound_ctrl:1
	v_add_f32_e32 v191, v198, v199
	s_waitcnt lgkmcnt(1)
	v_fma_f32 v204, -v154, v203, v188
	v_pk_mul_f32 v[198:199], v[76:77], v[104:105]
	v_mul_f32_e32 v206, v155, v204
	v_pk_fma_f32 v[198:199], v[78:79], v[102:103], v[198:199]
	v_pk_fma_f32 v[104:105], v[174:175], v[206:207], v[194:195] op_sel_hi:[1,0,1]
	v_pk_fma_f32 v[102:103], v[176:177], v[206:207], v[196:197] op_sel_hi:[1,0,1]
	v_pk_mul_f32 v[192:193], v[178:179], v[104:105]
	ds_read_b32 v189, v212 offset:11008
	v_pk_fma_f32 v[192:193], v[180:181], v[102:103], v[192:193]
	ds_read_b128 v[80:83], v211 offset:9216
	v_add_f32_e32 v203, v192, v193
	ds_read_b128 v[184:187], v211 offset:11520
	v_add_f32_dpp v202, v202, v202 quad_perm:[1,0,3,2] row_mask:0xf bank_mask:0xf bound_ctrl:1
	v_add_f32_dpp v203, v203, v203 quad_perm:[1,0,3,2] row_mask:0xf bank_mask:0xf bound_ctrl:1
	s_waitcnt lgkmcnt(3)
	v_pk_mul_f32 v[194:195], v[104:105], v[158:159] op_sel_hi:[1,0]
	v_add_f32_dpp v202, v202, v202 quad_perm:[2,3,0,1] row_mask:0xf bank_mask:0xf bound_ctrl:1
	v_add_f32_dpp v203, v203, v203 quad_perm:[2,3,0,1] row_mask:0xf bank_mask:0xf bound_ctrl:1
	v_pk_mul_f32 v[196:197], v[102:103], v[158:159] op_sel_hi:[1,0]
	v_add_f32_dpp v202, v202, v202 row_half_mirror row_mask:0xf bank_mask:0xf bound_ctrl:1
	v_add_f32_dpp v203, v203, v203 row_half_mirror row_mask:0xf bank_mask:0xf bound_ctrl:1
	ds_read_b64 v[168:169], v213 offset:37040
	v_add_f32_dpp v208, v202, v202 row_mirror row_mask:0xf bank_mask:0x2
	v_add_f32_dpp v203, v203, v203 row_mirror row_mask:0xf bank_mask:0xf bound_ctrl:1
	v_add_f32_e32 v202, v200, v201
	s_waitcnt lgkmcnt(1)
	v_fma_f32 v204, -v158, v203, v189
	v_pk_mul_f32 v[200:201], v[80:81], v[104:105]
	v_mul_f32_e32 v206, v159, v204
	v_pk_fma_f32 v[200:201], v[82:83], v[102:103], v[200:201]
	v_pk_fma_f32 v[104:105], v[178:179], v[206:207], v[194:195] op_sel_hi:[1,0,1]
	v_pk_fma_f32 v[102:103], v[180:181], v[206:207], v[196:197] op_sel_hi:[1,0,1]
	v_pk_mul_f32 v[192:193], v[184:185], v[104:105]
	ds_read_b32 v190, v212 offset:12032
	v_pk_fma_f32 v[192:193], v[186:187], v[102:103], v[192:193]
	ds_read_b128 v[84:87], v211 offset:10240
	v_add_f32_e32 v203, v192, v193
	ds_read_b128 v[92:95], v211 offset:12544
	v_add_f32_dpp v191, v191, v191 quad_perm:[1,0,3,2] row_mask:0xf bank_mask:0xf bound_ctrl:1
	v_add_f32_dpp v203, v203, v203 quad_perm:[1,0,3,2] row_mask:0xf bank_mask:0xf bound_ctrl:1
	s_waitcnt lgkmcnt(3)
	v_pk_mul_f32 v[194:195], v[104:105], v[168:169] op_sel_hi:[1,0]
	v_add_f32_dpp v191, v191, v191 quad_perm:[2,3,0,1] row_mask:0xf bank_mask:0xf bound_ctrl:1
	v_add_f32_dpp v203, v203, v203 quad_perm:[2,3,0,1] row_mask:0xf bank_mask:0xf bound_ctrl:1
	v_pk_mul_f32 v[196:197], v[102:103], v[168:169] op_sel_hi:[1,0]
	v_add_f32_dpp v191, v191, v191 row_half_mirror row_mask:0xf bank_mask:0xf bound_ctrl:1
	v_add_f32_dpp v203, v203, v203 row_half_mirror row_mask:0xf bank_mask:0xf bound_ctrl:1
	ds_read_b64 v[106:107], v213 offset:37056
	v_add_f32_dpp v209, v191, v191 row_mirror row_mask:0xf bank_mask:0x2
	v_add_f32_dpp v203, v203, v203 row_mirror row_mask:0xf bank_mask:0xf bound_ctrl:1
	v_add_f32_e32 v191, v198, v199
	s_waitcnt lgkmcnt(1)
	v_fma_f32 v204, -v168, v203, v190
	v_pk_mul_f32 v[198:199], v[84:85], v[104:105]
	v_mul_f32_e32 v206, v169, v204
	v_pk_fma_f32 v[198:199], v[86:87], v[102:103], v[198:199]
	v_pk_fma_f32 v[104:105], v[184:185], v[206:207], v[194:195] op_sel_hi:[1,0,1]
	v_pk_fma_f32 v[102:103], v[186:187], v[206:207], v[196:197] op_sel_hi:[1,0,1]
	v_pk_mul_f32 v[192:193], v[92:93], v[104:105]
	ds_read_b32 v182, v212 offset:13056
	v_pk_fma_f32 v[192:193], v[94:95], v[102:103], v[192:193]
	ds_read_b128 v[88:91], v211 offset:11264
	v_add_f32_e32 v203, v192, v193
	ds_read_b128 v[174:177], v211 offset:13568
	v_add_f32_dpp v202, v202, v202 quad_perm:[1,0,3,2] row_mask:0xf bank_mask:0xf bound_ctrl:1
	v_add_f32_dpp v203, v203, v203 quad_perm:[1,0,3,2] row_mask:0xf bank_mask:0xf bound_ctrl:1
	s_waitcnt lgkmcnt(3)
	v_pk_mul_f32 v[194:195], v[104:105], v[106:107] op_sel_hi:[1,0]
	v_add_f32_dpp v202, v202, v202 quad_perm:[2,3,0,1] row_mask:0xf bank_mask:0xf bound_ctrl:1
	v_add_f32_dpp v203, v203, v203 quad_perm:[2,3,0,1] row_mask:0xf bank_mask:0xf bound_ctrl:1
	v_pk_mul_f32 v[196:197], v[102:103], v[106:107] op_sel_hi:[1,0]
	v_add_f32_dpp v202, v202, v202 row_half_mirror row_mask:0xf bank_mask:0xf bound_ctrl:1
	v_add_f32_dpp v203, v203, v203 row_half_mirror row_mask:0xf bank_mask:0xf bound_ctrl:1
	ds_read_b64 v[154:155], v213 offset:37072
	v_add_f32_dpp v210, v202, v202 row_mirror row_mask:0xf bank_mask:0x2
	v_add_f32_dpp v203, v203, v203 row_mirror row_mask:0xf bank_mask:0xf bound_ctrl:1
	v_add_f32_e32 v202, v200, v201
	s_waitcnt lgkmcnt(1)
; template <int KG> __device__ __forceinline__ float redKG(float x) { x = red8d(x); if (KG == 16) x += dpp_rm(x); return x; }
; template <int MIX, int KPL, int KG>
; __device__ __forceinline__ float do_step(const StepIn<MIX, KPL>& s, float (&S)[KPL], const float gam) {
;   if (MIX == 0) {
;     float kS0 = 0.f, kS1 = 0.f, qS0 = 0.f, qS1 = 0.f;
; #pragma unroll
;     for (int i = 0; i < KPL; i += 2) { kS0 += s.k[i] * S[i]; kS1 += s.k[i + 1] * S[i + 1]; qS0 += s.q[i] * S[i]; qS1 += s.q[i + 1] * S[i + 1]; }
;     const float kS = redKG<KG>(kS0 + kS1), qS = redKG<KG>(qS0 + qS1);
;     const float w = s.be * (s.v - s.a * kS);
; #pragma unroll
;     for (int i = 0; i < KPL; ++i) S[i] = s.a * S[i] + s.k[i] * w;
;     return s.a * qS + s.qk * w;
; template <int MIX>
; __device__ __forceinline__ void scan_part(const Params& p, const int layer, const int smp, const int b0, const int bstep, const int bend, const int h, const int part, char* lds, const int tid) {
;     ...
;       for (int t = 0; t < ntok; t += 2) {
;         load_step<MIX, KPL>(qkdv, scal, t + 1, kg, col, sb);
;         __builtin_amdgcn_sched_barrier(0);
;         const float oa = do_step<MIX, KPL, KG>(sa, S, gam);
;         osave = (kg == (t & (KG - 1))) ? oa : osave;
;         load_step<MIX, KPL>(qkdv, scal, min(t + 2, ntok - 1), kg, col, sa);
;         __builtin_amdgcn_sched_barrier(0);
;         const float ob = do_step<MIX, KPL, KG>(sb, S, gam);
;         osave = (kg == ((t + 1) & (KG - 1))) ? ob : osave;
;         if (((t + 2) & (KG - 1)) == 0) obuf[(t + 2 - KG + kg) * CW + col] = osave;
;       }
	v_fma_f32 v204, -v106, v203, v182
	v_pk_mul_f32 v[200:201], v[88:89], v[104:105]
	v_mul_f32_e32 v206, v107, v204
	v_pk_fma_f32 v[200:201], v[90:91], v[102:103], v[200:201]
	v_pk_fma_f32 v[104:105], v[92:93], v[206:207], v[194:195] op_sel_hi:[1,0,1]
	v_pk_fma_f32 v[102:103], v[94:95], v[206:207], v[196:197] op_sel_hi:[1,0,1]
	v_pk_mul_f32 v[192:193], v[174:175], v[104:105]
	ds_read_b32 v188, v212 offset:14080
	v_pk_fma_f32 v[192:193], v[176:177], v[102:103], v[192:193]
	ds_read_b128 v[76:79], v211 offset:12288
	v_add_f32_e32 v203, v192, v193
	ds_read_b128 v[178:181], v211 offset:14592
	v_add_f32_dpp v191, v191, v191 quad_perm:[1,0,3,2] row_mask:0xf bank_mask:0xf bound_ctrl:1
	v_add_f32_dpp v203, v203, v203 quad_perm:[1,0,3,2] row_mask:0xf bank_mask:0xf bound_ctrl:1
	s_waitcnt lgkmcnt(3)
	v_pk_mul_f32 v[194:195], v[104:105], v[154:155] op_sel_hi:[1,0]
	v_add_f32_dpp v191, v191, v191 quad_perm:[2,3,0,1] row_mask:0xf bank_mask:0xf bound_ctrl:1
	v_add_f32_dpp v203, v203, v203 quad_perm:[2,3,0,1] row_mask:0xf bank_mask:0xf bound_ctrl:1
	v_pk_mul_f32 v[196:197], v[102:103], v[154:155] op_sel_hi:[1,0]
	v_add_f32_dpp v191, v191, v191 row_half_mirror row_mask:0xf bank_mask:0xf bound_ctrl:1
	v_add_f32_dpp v203, v203, v203 row_half_mirror row_mask:0xf bank_mask:0xf bound_ctrl:1
	ds_read_b64 v[158:159], v213 offset:37088
	v_add_f32_dpp v205, v191, v191 row_mirror row_mask:0xf bank_mask:0x4
	v_add_f32_dpp v203, v203, v203 row_mirror row_mask:0xf bank_mask:0xf bound_ctrl:1
	v_add_f32_e32 v191, v198, v199
	s_waitcnt lgkmcnt(1)
	v_fma_f32 v204, -v154, v203, v188
	v_pk_mul_f32 v[198:199], v[76:77], v[104:105]
	v_mul_f32_e32 v206, v155, v204
	v_pk_fma_f32 v[198:199], v[78:79], v[102:103], v[198:199]
	v_pk_fma_f32 v[104:105], v[174:175], v[206:207], v[194:195] op_sel_hi:[1,0,1]
	v_pk_fma_f32 v[102:103], v[176:177], v[206:207], v[196:197] op_sel_hi:[1,0,1]
	v_pk_mul_f32 v[192:193], v[178:179], v[104:105]
	ds_read_b32 v189, v212 offset:15104
	v_pk_fma_f32 v[192:193], v[180:181], v[102:103], v[192:193]
	v_add_f32_dpp v202, v202, v202 quad_perm:[1,0,3,2] row_mask:0xf bank_mask:0xf bound_ctrl:1
	ds_read_b128 v[80:83], v211 offset:13312
	v_add_f32_e32 v203, v192, v193
	ds_read_b128 v[184:187], v211 offset:15616
	v_add_f32_dpp v202, v202, v202 quad_perm:[2,3,0,1] row_mask:0xf bank_mask:0xf bound_ctrl:1
	v_add_f32_dpp v203, v203, v203 quad_perm:[1,0,3,2] row_mask:0xf bank_mask:0xf bound_ctrl:1
	v_add_f32_dpp v191, v191, v191 quad_perm:[1,0,3,2] row_mask:0xf bank_mask:0xf bound_ctrl:1
	v_add_f32_dpp v202, v202, v202 row_half_mirror row_mask:0xf bank_mask:0xf bound_ctrl:1
	v_add_f32_dpp v203, v203, v203 quad_perm:[2,3,0,1] row_mask:0xf bank_mask:0xf bound_ctrl:1
	s_waitcnt lgkmcnt(3)
	v_pk_mul_f32 v[194:195], v[104:105], v[158:159] op_sel_hi:[1,0]
	v_add_f32_dpp v208, v202, v202 row_mirror row_mask:0xf bank_mask:0x4
	v_add_f32_dpp v203, v203, v203 row_half_mirror row_mask:0xf bank_mask:0xf bound_ctrl:1
	v_add_f32_e32 v202, v200, v201
	v_pk_mul_f32 v[196:197], v[102:103], v[158:159] op_sel_hi:[1,0]
	v_add_f32_dpp v203, v203, v203 row_mirror row_mask:0xf bank_mask:0xf bound_ctrl:1
	v_add_f32_dpp v202, v202, v202 quad_perm:[1,0,3,2] row_mask:0xf bank_mask:0xf bound_ctrl:1
	s_waitcnt lgkmcnt(0)
; template <int KG> __device__ __forceinline__ float redKG(float x) { x = red8d(x); if (KG == 16) x += dpp_rm(x); return x; }
; template <int MIX, int KPL, int KG>
; __device__ __forceinline__ float do_step(const StepIn<MIX, KPL>& s, float (&S)[KPL], const float gam) {
;   if (MIX == 0) {
;     float kS0 = 0.f, kS1 = 0.f, qS0 = 0.f, qS1 = 0.f;
; #pragma unroll
;     for (int i = 0; i < KPL; i += 2) { kS0 += s.k[i] * S[i]; kS1 += s.k[i + 1] * S[i + 1]; qS0 += s.q[i] * S[i]; qS1 += s.q[i + 1] * S[i + 1]; }
;     const float kS = redKG<KG>(kS0 + kS1), qS = redKG<KG>(qS0 + qS1);
;     const float w = s.be * (s.v - s.a * kS);
; #pragma unroll
;     for (int i = 0; i < KPL; ++i) S[i] = s.a * S[i] + s.k[i] * w;
;     return s.a * qS + s.qk * w;
; template <int MIX>
; __device__ __forceinline__ void scan_part(const Params& p, const int layer, const int smp, const int b0, const int bstep, const int bend, const int h, const int part, char* lds, const int tid) {
;     ...
;       for (int t = 0; t < ntok; t += 2) {
;         load_step<MIX, KPL>(qkdv, scal, t + 1, kg, col, sb);
;         __builtin_amdgcn_sched_barrier(0);
;         const float oa = do_step<MIX, KPL, KG>(sa, S, gam);
;         osave = (kg == (t & (KG - 1))) ? oa : osave;
;         load_step<MIX, KPL>(qkdv, scal, min(t + 2, ntok - 1), kg, col, sa);
;         __builtin_amdgcn_sched_barrier(0);
;         const float ob = do_step<MIX, KPL, KG>(sb, S, gam);
;         osave = (kg == ((t + 1) & (KG - 1))) ? ob : osave;
;         if (((t + 2) & (KG - 1)) == 0) obuf[(t + 2 - KG + kg) * CW + col] = osave;
;       }
	v_fma_f32 v204, -v158, v203, v189
	v_pk_mul_f32 v[200:201], v[80:81], v[104:105]
	v_mul_f32_e32 v206, v159, v204
	v_pk_fma_f32 v[200:201], v[82:83], v[102:103], v[200:201]
	v_pk_fma_f32 v[104:105], v[178:179], v[206:207], v[194:195] op_sel_hi:[1,0,1]
	v_add_f32_dpp v191, v191, v191 quad_perm:[2,3,0,1] row_mask:0xf bank_mask:0xf bound_ctrl:1
	v_add_f32_dpp v202, v202, v202 quad_perm:[2,3,0,1] row_mask:0xf bank_mask:0xf bound_ctrl:1
	v_pk_fma_f32 v[102:103], v[180:181], v[206:207], v[196:197] op_sel_hi:[1,0,1]
	v_pk_mul_f32 v[192:193], v[184:185], v[104:105]
	ds_read_b64 v[168:169], v213 offset:37104
	ds_read_b32 v190, v212 offset:16128
	v_pk_fma_f32 v[192:193], v[186:187], v[102:103], v[192:193]
	ds_read_b128 v[84:87], v211 offset:14336
	v_add_f32_e32 v203, v192, v193
	v_add_f32_dpp v191, v191, v191 row_half_mirror row_mask:0xf bank_mask:0xf bound_ctrl:1
	v_add_f32_dpp v202, v202, v202 row_half_mirror row_mask:0xf bank_mask:0xf bound_ctrl:1
	ds_read_b128 v[88:91], v211 offset:15360
	v_add_f32_dpp v203, v203, v203 quad_perm:[1,0,3,2] row_mask:0xf bank_mask:0xf bound_ctrl:1
	v_add_f32_dpp v209, v191, v191 row_mirror row_mask:0xf bank_mask:0x4
	v_add_f32_dpp v210, v202, v202 row_mirror row_mask:0xf bank_mask:0x4
	v_add_f32_e32 v191, v198, v199
	v_add_f32_e32 v202, v200, v201
	v_add_f32_dpp v203, v203, v203 quad_perm:[2,3,0,1] row_mask:0xf bank_mask:0xf bound_ctrl:1
	v_add_f32_dpp v191, v191, v191 quad_perm:[1,0,3,2] row_mask:0xf bank_mask:0xf bound_ctrl:1
	v_add_f32_dpp v202, v202, v202 quad_perm:[1,0,3,2] row_mask:0xf bank_mask:0xf bound_ctrl:1
	v_add_f32_dpp v203, v203, v203 row_half_mirror row_mask:0xf bank_mask:0xf bound_ctrl:1
	v_add_f32_dpp v191, v191, v191 quad_perm:[2,3,0,1] row_mask:0xf bank_mask:0xf bound_ctrl:1
	v_add_f32_dpp v202, v202, v202 quad_perm:[2,3,0,1] row_mask:0xf bank_mask:0xf bound_ctrl:1
	v_add_f32_dpp v203, v203, v203 row_mirror row_mask:0xf bank_mask:0xf bound_ctrl:1
	s_waitcnt lgkmcnt(0)
	v_fma_f32 v204, -v168, v203, v190
	v_add_f32_dpp v191, v191, v191 row_half_mirror row_mask:0xf bank_mask:0xf bound_ctrl:1
	v_add_f32_dpp v202, v202, v202 row_half_mirror row_mask:0xf bank_mask:0xf bound_ctrl:1
	v_pk_mul_f32 v[198:199], v[84:85], v[104:105]
	v_pk_mul_f32 v[194:195], v[104:105], v[168:169] op_sel_hi:[1,0]
	v_mul_f32_e32 v206, v169, v204
	v_pk_fma_f32 v[198:199], v[86:87], v[102:103], v[198:199]
	v_pk_mul_f32 v[196:197], v[102:103], v[168:169] op_sel_hi:[1,0]
	v_pk_fma_f32 v[104:105], v[184:185], v[206:207], v[194:195] op_sel_hi:[1,0,1]
	v_pk_fma_f32 v[102:103], v[186:187], v[206:207], v[196:197] op_sel_hi:[1,0,1]
	v_pk_mul_f32 v[200:201], v[88:89], v[104:105]
	v_add_f32_dpp v205, v191, v191 row_mirror row_mask:0xf bank_mask:0x8
	v_add_f32_dpp v208, v202, v202 row_mirror row_mask:0xf bank_mask:0x8
	v_pk_fma_f32 v[200:201], v[90:91], v[102:103], v[200:201]
	v_add_f32_e32 v191, v198, v199
	v_add_f32_e32 v202, v200, v201
	ds_read_b128 v[92:95], v211 offset:16640
	v_add_f32_dpp v191, v191, v191 quad_perm:[1,0,3,2] row_mask:0xf bank_mask:0xf bound_ctrl:1
	v_add_f32_dpp v202, v202, v202 quad_perm:[1,0,3,2] row_mask:0xf bank_mask:0xf bound_ctrl:1
	ds_read_b64 v[106:107], v213 offset:37120
	v_add_f32_dpp v191, v191, v191 quad_perm:[2,3,0,1] row_mask:0xf bank_mask:0xf bound_ctrl:1
	v_add_f32_dpp v202, v202, v202 quad_perm:[2,3,0,1] row_mask:0xf bank_mask:0xf bound_ctrl:1
	ds_read_b32 v182, v212 offset:17152
	v_add_f32_dpp v191, v191, v191 row_half_mirror row_mask:0xf bank_mask:0xf bound_ctrl:1
	v_add_f32_dpp v202, v202, v202 row_half_mirror row_mask:0xf bank_mask:0xf bound_ctrl:1
	ds_read_b128 v[76:79], v211 offset:16384
	v_add_f32_dpp v209, v191, v191 row_mirror row_mask:0xf bank_mask:0x8
	v_add_f32_dpp v210, v202, v202 row_mirror row_mask:0xf bank_mask:0x8
	ds_read_b128 v[174:177], v211 offset:17664
	ds_read_b64 v[154:155], v213 offset:37136
	ds_read_b32 v188, v212 offset:18176
	ds_read_b128 v[80:83], v211 offset:17408
	ds_write_b32 v214, v205 offset:32768
	ds_write_b32 v214, v208 offset:32832
	ds_write_b32 v214, v209 offset:32896
	ds_write_b32 v214, v210 offset:32960
	v_add_u32_e32 v211, 0x4000, v211
	v_add_u32_e32 v212, 0x4000, v212
	v_add_u32_e32 v213, 0x100, v213
	v_add_u32_e32 v214, 0x400, v214
	s_sub_i32 s50, s50, 1
	s_cmp_lg_u32 s50, 0
	s_cbranch_scc1 .Lscan0p_blk
